# first block-0 P.V MFMA issued ahead of the score chain (its V fragments requested before the K fragments)
# speedup vs baseline: 1.0052x; 1.0007x over previous
; #define SBAR() __builtin_amdgcn_sched_barrier(0)
; #define KDMA(k0, b) do { const char* g_ = (const char*)(Kh + (long)(k0) * DM); char* l_ = K_lds + (b) * 16384 + wu * 1024; \
;     DMA16(g_ + koff[0], l_); DMA16(g_ + koff[1], l_ + 8192); } while (0)
; #define VDMA(k0, b) do { const char* g_ = (const char*)(Vh + (long)(k0) * DM); char* l_ = V_lds + (b) * 32768 + wu * 1024; \
;     DMA16(g_ + voff[0], l_); DMA16(g_ + voff[1], l_ + 8192); DMA16(g_ + voff[0] + 256, l_ + 16384); DMA16(g_ + voff[1] + 256, l_ + 16384 + 8192); } while (0)
; #define VRD(D0, X) do { X##0 = tr_read<v_rd_off(D0, 0, 0)>(vb); X##1 = tr_read<v_rd_off(D0, 0, 1)>(vb); X##2 = tr_read<v_rd_off(D0, 1, 0)>(vb); X##3 = tr_read<v_rd_off(D0, 1, 1)>(vb); \
;     X##4 = tr_read<v_rd_off(D0, 2, 0)>(vb); X##5 = tr_read<v_rd_off(D0, 2, 1)>(vb); X##6 = tr_read<v_rd_off(D0, 3, 0)>(vb); X##7 = tr_read<v_rd_off(D0, 3, 1)>(vb); } while (0)
; template <int PROBE, int MODE>
; DI void dattn_body(const u16* __restrict__ Qb, const u16* __restrict__ Kh, const u16* __restrict__ Vh, u16* __restrict__ Ob, const u16* __restrict__ O1, float lam, const float* __restrict__ subg, int seq, int q0, float kmax2, char* lds) {
;     ...
;   for (int j = 0; j < NT; ++j) {
;     const bool more = j + 1 < NT;
;     if (!(PROBE & 1)) {
;       if (j + 2 < NT) KDMA((j + 2) * KVBLK, j & 1);
;       if (more) VDMA((j + 1) * KVBLK, (j + 1) & 1);
;     }
;     bf16x8 kf[8];
;     if (more) { const char* Ks_ = K_lds + ((j + 1) & 1) * 16384;
; #pragma unroll
;       for (int d0 = 0; d0 < 8; ++d0) kf[d0] = *reinterpret_cast<const bf16x8*>(Ks_ + KSWZ(32 * kh + r32, (d0 * 16 + hi * 8) * 2)); }
;     const bf16x8 pb0 = *(const bf16x8*)(pr + (j & 1) * 16384), pb1 = *(const bf16x8*)(pr + (j & 1) * 16384 + 16);
;     const int vb = vb0 + (j & 1) * 32768;
;     s16x4 va0, va1, va2, va3, va4, va5, va6, va7, vc0, vc1, vc2, vc3, vc4, vc5, vc6, vc7;
;     VRD(0, va);
;     if (more) { asm volatile("s_waitcnt lgkmcnt(10)" ::: "memory"); SBAR();
;       if (!(PROBE & 4)) { S = f32x16{};
; #pragma unroll
;       for (int d0 = 0; d0 < 8; ++d0) S = __builtin_amdgcn_mfma_f32_32x32x16_bf16(kf[d0], qr[d0], S, 0, 0, 0); }
;       SBAR(); }
;     const bf16x8 A0 = kh ? pb0 : po0, A1 = kh ? pb1 : po1, A2 = kh ? po0 : pb0, A3 = kh ? po1 : pb1;
;     SMX_SETUP(j + 1)
;     ...
;     LWAIT(); VRD(1, vc); VMMP(0, va); SMXP(0);
;     LWAIT(); VRD(2, va); VMMP(1, vc); SMXP(1);
.Lfast0:
	s_sub_i32 s72, s18, 64
	s_and_b32 s101, s25, 0x4000
	s_addk_i32 s25, 0x4000
	s_and_b32 s19, s25, 0x4000
	s_and_b32 s48, s55, 1
	v_lshl_add_u32 v68, s48, 14, v210
	ds_read_b128 v[162:165], v68
	ds_read_b128 v[166:169], v68 offset:16
	s_bfe_u32 s100, s85, 0x1000a
	s_lshl_b32 s100, s100, 13
	s_lshl_b32 s48, s48, 15
	s_sub_i32 s74, s48, s100
	s_add_i32 s48, s48, s100
	v_add_u32_e32 v216, s48, v212
	v_add_u32_e32 v233, s74, v212
	v_add_u32_e32 v68, s19, v213
	v_add_u32_e32 v64, v68, v198
	v_add_u32_e32 v69, v68, v199
	ds_read_b64_tr_b16 v[234:235], v216 offset:0
	ds_read_b64_tr_b16 v[236:237], v216 offset:0x800
	ds_read_b128 v[64:67], v64
	ds_read_b128 v[118:121], v69
	v_add_u32_e32 v69, v68, v200
	v_add_u32_e32 v70, v68, v201
	ds_read_b128 v[122:125], v69
	ds_read_b128 v[126:129], v70
	ds_read_b64_tr_b16 v[238:239], v216 offset:0x1000
	ds_read_b64_tr_b16 v[240:241], v216 offset:0x1800
	v_add_u32_e32 v69, v68, v202
	v_add_u32_e32 v70, v68, v203
	ds_read_b128 v[134:137], v69
	ds_read_b128 v[138:141], v70
	v_add_u32_e32 v142, v68, v204
	v_add_u32_e32 v146, v68, v205
	s_cmp_gt_i32 s72, s87
	s_cselect_b32 s100, s21, s20
	v_sub_f32_e32 v160, s100, v158
	s_lshl_b32 s48, s72, 12
	s_add_u32 s48, s16, s48
	s_addc_u32 s49, s17, 0
	s_add_u32 s74, s48, 0x100
	s_addc_u32 s75, s49, 0
	s_and_b32 s100, s54, 0x8000
	s_add_i32 s100, s85, s100
	s_waitcnt lgkmcnt(8)
	v_mfma_f32_32x32x16_bf16 v[0:15], v[114:117], v[234:237], v[0:15]
	ds_read_b64_tr_b16 v[242:243], v233 offset:0x2000
	ds_read_b64_tr_b16 v[244:245], v233 offset:0x2800
	s_waitcnt lgkmcnt(9)
	v_mfma_f32_32x32x16_bf16 v[64:79], v[64:67], v[82:85], 0
	ds_read_b128 v[142:145], v142
	ds_read_b128 v[146:149], v146
	s_waitcnt lgkmcnt(10)
	v_mfma_f32_32x32x16_bf16 v[64:79], v[118:121], v[86:89], v[64:79]
	ds_read_b64_tr_b16 v[246:247], v233 offset:0x3000
	ds_read_b64_tr_b16 v[248:249], v233 offset:0x3800
	s_waitcnt lgkmcnt(11)
	v_mfma_f32_32x32x16_bf16 v[64:79], v[122:125], v[90:93], v[64:79]
	s_waitcnt lgkmcnt(10)
	v_mfma_f32_32x32x16_bf16 v[64:79], v[126:129], v[94:97], v[64:79]
	ds_read_b64_tr_b16 v[126:127], v233 offset:0x3200
	ds_read_b64_tr_b16 v[128:129], v233 offset:0x3a00
	s_waitcnt lgkmcnt(10)
	v_mfma_f32_32x32x16_bf16 v[0:15], v[130:133], v[238:241], v[0:15]
	s_mov_b32 m0, s100
	s_waitcnt lgkmcnt(9)
	v_mfma_f32_32x32x16_bf16 v[64:79], v[134:137], v[98:101], v[64:79]
	global_load_lds_dwordx4 v176, s[48:49]
	ds_read_b64_tr_b16 v[134:135], v233 offset:0x2200
	ds_read_b64_tr_b16 v[136:137], v233 offset:0x2a00
	s_add_i32 m0, s100, 0x2000
	s_waitcnt lgkmcnt(10)
	v_mfma_f32_32x32x16_bf16 v[64:79], v[138:141], v[102:105], v[64:79]
	global_load_lds_dwordx4 v156, s[48:49]
	ds_read_b64_tr_b16 v[138:139], v216 offset:0x200
	ds_read_b64_tr_b16 v[140:141], v216 offset:0xa00
	s_add_i32 m0, s100, 0x4000
	s_waitcnt lgkmcnt(10)
	v_mfma_f32_32x32x16_bf16 v[0:15], v[162:165], v[242:245], v[0:15]
	global_load_lds_dwordx4 v176, s[74:75]
	s_add_i32 m0, s100, 0x6000
	s_waitcnt lgkmcnt(9)
	v_mfma_f32_32x32x16_bf16 v[64:79], v[142:145], v[106:109], v[64:79]
	ds_read_b64_tr_b16 v[142:143], v216 offset:0x1200
	ds_read_b64_tr_b16 v[144:145], v216 offset:0x1a00
	s_waitcnt lgkmcnt(10)
	v_mfma_f32_32x32x16_bf16 v[64:79], v[146:149], v[110:113], v[64:79]
	global_load_lds_dwordx4 v156, s[74:75]
	s_waitcnt lgkmcnt(8)
	v_mfma_f32_32x32x16_bf16 v[0:15], v[166:169], v[246:249], v[0:15]
	s_add_i32 s48, s55, 2
	s_cmp_ge_u32 s48, s11
	s_cbranch_scc1 .Lfast0_k_done
	s_lshl_b32 s48, s18, 12
	s_add_u32 s48, s14, s48
	s_addc_u32 s49, s15, 0
	s_add_i32 s100, s82, s101
	s_mov_b32 m0, s100
	s_nop 0
	global_load_lds_dwordx4 v152, s[48:49]
	s_add_i32 m0, s100, 0x2000
	s_nop 0
	global_load_lds_dwordx4 v154, s[48:49]

; #define SBAR() __builtin_amdgcn_sched_barrier(0)
; #define KDMA(k0, b) do { const char* g_ = (const char*)(Kh + (long)(k0) * DM); char* l_ = K_lds + (b) * 16384 + wu * 1024; \
;     DMA16(g_ + koff[0], l_); DMA16(g_ + koff[1], l_ + 8192); } while (0)
; #define VDMA(k0, b) do { const char* g_ = (const char*)(Vh + (long)(k0) * DM); char* l_ = V_lds + (b) * 32768 + wu * 1024; \
;     DMA16(g_ + voff[0], l_); DMA16(g_ + voff[1], l_ + 8192); DMA16(g_ + voff[0] + 256, l_ + 16384); DMA16(g_ + voff[1] + 256, l_ + 16384 + 8192); } while (0)
; #define VRD(D0, X) do { X##0 = tr_read<v_rd_off(D0, 0, 0)>(vb); X##1 = tr_read<v_rd_off(D0, 0, 1)>(vb); X##2 = tr_read<v_rd_off(D0, 1, 0)>(vb); X##3 = tr_read<v_rd_off(D0, 1, 1)>(vb); \
;     X##4 = tr_read<v_rd_off(D0, 2, 0)>(vb); X##5 = tr_read<v_rd_off(D0, 2, 1)>(vb); X##6 = tr_read<v_rd_off(D0, 3, 0)>(vb); X##7 = tr_read<v_rd_off(D0, 3, 1)>(vb); } while (0)
; template <int PROBE, int MODE>
; DI void dattn_body(const u16* __restrict__ Qb, const u16* __restrict__ Kh, const u16* __restrict__ Vh, u16* __restrict__ Ob, const u16* __restrict__ O1, float lam, const float* __restrict__ subg, int seq, int q0, float kmax2, char* lds) {
;     ...
;   for (int j = 0; j < NT; ++j) {
;     const bool more = j + 1 < NT;
;     if (!(PROBE & 1)) {
;       if (j + 2 < NT) KDMA((j + 2) * KVBLK, j & 1);
;       if (more) VDMA((j + 1) * KVBLK, (j + 1) & 1);
;     }
;     bf16x8 kf[8];
;     if (more) { const char* Ks_ = K_lds + ((j + 1) & 1) * 16384;
; #pragma unroll
;       for (int d0 = 0; d0 < 8; ++d0) kf[d0] = *reinterpret_cast<const bf16x8*>(Ks_ + KSWZ(32 * kh + r32, (d0 * 16 + hi * 8) * 2)); }
;     const bf16x8 pb0 = *(const bf16x8*)(pr + (j & 1) * 16384), pb1 = *(const bf16x8*)(pr + (j & 1) * 16384 + 16);
;     const int vb = vb0 + (j & 1) * 32768;
;     s16x4 va0, va1, va2, va3, va4, va5, va6, va7, vc0, vc1, vc2, vc3, vc4, vc5, vc6, vc7;
;     VRD(0, va);
;     if (more) { asm volatile("s_waitcnt lgkmcnt(10)" ::: "memory"); SBAR();
;       if (!(PROBE & 4)) { S = f32x16{};
; #pragma unroll
;       for (int d0 = 0; d0 < 8; ++d0) S = __builtin_amdgcn_mfma_f32_32x32x16_bf16(kf[d0], qr[d0], S, 0, 0, 0); }
;       SBAR(); }
;     const bf16x8 A0 = kh ? pb0 : po0, A1 = kh ? pb1 : po1, A2 = kh ? po0 : pb0, A3 = kh ? po1 : pb1;
;     SMX_SETUP(j + 1)
;     ...
;     LWAIT(); VRD(1, vc); VMMP(0, va); SMXP(0);
;     LWAIT(); VRD(2, va); VMMP(1, vc); SMXP(1);
.Lfast1:
	s_sub_i32 s72, s0, 64
	s_and_b32 s101, s24, 0x4000
	s_addk_i32 s24, 0x4000
	s_and_b32 s1, s24, 0x4000
	s_and_b32 s4, s40, 1
	v_lshl_add_u32 v68, s4, 14, v209
	ds_read_b128 v[162:165], v68
	ds_read_b128 v[166:169], v68 offset:16
	s_bfe_u32 s100, s39, 0x1000a
	s_lshl_b32 s100, s100, 13
	s_lshl_b32 s4, s4, 15
	s_sub_i32 s18, s4, s100
	s_add_i32 s4, s4, s100
	v_add_u32_e32 v215, s4, v211
	v_add_u32_e32 v233, s18, v211
	v_add_u32_e32 v68, s1, v212
	v_add_u32_e32 v64, v68, v196
	v_add_u32_e32 v69, v68, v198
	ds_read_b64_tr_b16 v[234:235], v215 offset:0
	ds_read_b64_tr_b16 v[236:237], v215 offset:0x800
	ds_read_b128 v[64:67], v64
	ds_read_b128 v[118:121], v69
	v_add_u32_e32 v69, v68, v199
	v_add_u32_e32 v70, v68, v200
	ds_read_b128 v[122:125], v69
	ds_read_b128 v[126:129], v70
	ds_read_b64_tr_b16 v[238:239], v215 offset:0x1000
	ds_read_b64_tr_b16 v[240:241], v215 offset:0x1800
	v_add_u32_e32 v69, v68, v201
	v_add_u32_e32 v70, v68, v202
	ds_read_b128 v[134:137], v69
	ds_read_b128 v[138:141], v70
	v_add_u32_e32 v142, v68, v203
	v_add_u32_e32 v146, v68, v204
	s_cmp_gt_i32 s72, s87
	s_cselect_b32 s100, s21, s20
	v_sub_f32_e32 v160, s100, v158
	s_lshl_b32 s4, s72, 12
	s_add_u32 s4, s16, s4
	s_addc_u32 s5, s17, 0
	s_add_u32 s18, s4, 0x100
	s_addc_u32 s19, s5, 0
	s_and_b32 s100, s25, 0x8000
	s_add_i32 s100, s39, s100
	s_waitcnt lgkmcnt(8)
	v_mfma_f32_32x32x16_bf16 v[0:15], v[114:117], v[234:237], v[0:15]
	ds_read_b64_tr_b16 v[242:243], v233 offset:0x2000
	ds_read_b64_tr_b16 v[244:245], v233 offset:0x2800
	s_waitcnt lgkmcnt(9)
	v_mfma_f32_32x32x16_bf16 v[64:79], v[64:67], v[82:85], 0
	ds_read_b128 v[142:145], v142
	ds_read_b128 v[146:149], v146
	s_waitcnt lgkmcnt(10)
	v_mfma_f32_32x32x16_bf16 v[64:79], v[118:121], v[86:89], v[64:79]
	ds_read_b64_tr_b16 v[246:247], v233 offset:0x3000
	ds_read_b64_tr_b16 v[248:249], v233 offset:0x3800
	s_waitcnt lgkmcnt(11)
	v_mfma_f32_32x32x16_bf16 v[64:79], v[122:125], v[90:93], v[64:79]
	s_waitcnt lgkmcnt(10)
	v_mfma_f32_32x32x16_bf16 v[64:79], v[126:129], v[94:97], v[64:79]
	ds_read_b64_tr_b16 v[126:127], v233 offset:0x3200
	ds_read_b64_tr_b16 v[128:129], v233 offset:0x3a00
	s_waitcnt lgkmcnt(10)
	v_mfma_f32_32x32x16_bf16 v[0:15], v[130:133], v[238:241], v[0:15]
	s_mov_b32 m0, s100
	s_waitcnt lgkmcnt(9)
	v_mfma_f32_32x32x16_bf16 v[64:79], v[134:137], v[98:101], v[64:79]
	global_load_lds_dwordx4 v152, s[4:5]
	ds_read_b64_tr_b16 v[134:135], v233 offset:0x2200
	ds_read_b64_tr_b16 v[136:137], v233 offset:0x2a00
	s_add_i32 m0, s100, 0x2000
	s_waitcnt lgkmcnt(10)
	v_mfma_f32_32x32x16_bf16 v[64:79], v[138:141], v[102:105], v[64:79]
	global_load_lds_dwordx4 v156, s[4:5]
	ds_read_b64_tr_b16 v[138:139], v215 offset:0x200
	ds_read_b64_tr_b16 v[140:141], v215 offset:0xa00
	s_add_i32 m0, s100, 0x4000
	s_waitcnt lgkmcnt(10)
	v_mfma_f32_32x32x16_bf16 v[0:15], v[162:165], v[242:245], v[0:15]
	global_load_lds_dwordx4 v152, s[18:19]
	s_add_i32 m0, s100, 0x6000
	s_waitcnt lgkmcnt(9)
	v_mfma_f32_32x32x16_bf16 v[64:79], v[142:145], v[106:109], v[64:79]
	ds_read_b64_tr_b16 v[142:143], v215 offset:0x1200
	ds_read_b64_tr_b16 v[144:145], v215 offset:0x1a00
	s_waitcnt lgkmcnt(10)
	v_mfma_f32_32x32x16_bf16 v[64:79], v[146:149], v[110:113], v[64:79]
	global_load_lds_dwordx4 v156, s[18:19]
	s_waitcnt lgkmcnt(8)
	v_mfma_f32_32x32x16_bf16 v[0:15], v[166:169], v[246:249], v[0:15]
	s_add_i32 s4, s40, 2
	s_cmp_ge_u32 s4, s11
	s_cbranch_scc1 .Lfast1_k_done
	s_lshl_b32 s4, s0, 12
	s_add_u32 s4, s14, s4
	s_addc_u32 s5, s15, 0
	s_add_u32 s4, s4, 0x100
	s_addc_u32 s5, s5, 0
	s_add_i32 s100, s38, s101
	s_mov_b32 m0, s100
	s_nop 0
	global_load_lds_dwordx4 v176, s[4:5]
	s_add_i32 m0, s100, 0x2000
	s_nop 0
	global_load_lds_dwordx4 v154, s[4:5]
